# loop-edge edit in the C tile loop: loop test moved in front of the tile-end barrier so only the branch follows the release; rest as v43
# speedup vs baseline: 1.0026x; 1.0026x over previous
; DI float ex2(float x) { return __builtin_amdgcn_exp2f(x); }
; #define MFMA32(a, b, c) __builtin_amdgcn_mfma_f32_32x32x16_bf16((a), (b), (c), 0, 0, 0)
; template <int MODE>
; DI void attn_unit(unsigned char* lds, const AttnParams& ap, int b, int h, int qb, int tid) {
;     ...
;     if (MODE == 1) {
; #pragma unroll
;       for (int kh = 0; kh < 2; ++kh) {
;         const bf16_t* kb = Ks + (32 * kh + r32) * 72 + 8 * hi;
;         bf16x8 p0[2], p1[2];
;         { f32x16 s0 = splat16(ap.negM);
;           s0 = MFMA32(*(const bf16x8*)(kb), qf[0], s0); s0 = MFMA32(*(const bf16x8*)(kb + 16), qf[1], s0);
; #pragma unroll
;           for (int i = 0; i < 16; ++i) { s0[i] = ex2(s0[i]); l0 += s0[i]; }
;           p0[0] = pack8(s0, 0); p0[1] = pack8(s0, 1); }
;         { f32x16 s1 = splat16(ap.negM);
;           s1 = MFMA32(*(const bf16x8*)(kb + 32), qf[2], s1); s1 = MFMA32(*(const bf16x8*)(kb + 48), qf[3], s1);
; #pragma unroll
;           for (int i = 0; i < 16; ++i) { s1[i] = ex2(s1[i]); l1 += s1[i]; }
;           p1[0] = pack8(s1, 0); p1[1] = pack8(s1, 1); }
; #pragma unroll
;         for (int kk = 0; kk < 2; ++kk) {
; #pragma unroll
;           for (int eb = 0; eb < 2; ++eb) { const bf16_t* vb = Vs + (32 * eb + r32) * 72 + 32 * kh + 16 * kk + 8 * hi; const bf16x8 vf = *(const bf16x8*)vb;
;             O0[eb] = MFMA32(vf, p0[kk], O0[eb]); O1[eb] = MFMA32(vf, p1[kk], O1[eb]); } }
;       }
.Lc_tile_ph0:
	s_add_i32 m0, s0, 32768
	s_add_i32 s4, s4, 1
	global_load_lds_dwordx4 v32, s[2:3]
	s_add_i32 m0, s0, 40960
	s_add_u32 s2, s2, 0x68800
	s_addc_u32 s3, s3, 0
	global_load_lds_dwordx4 v157, s[10:11]
	s_add_u32 s10, s10, 0x2000
	s_addc_u32 s11, s11, 0
	s_waitcnt lgkmcnt(0)
	v_mfma_f32_32x32x16_bf16 v[116:131], v[166:169], v[38:41], v[48:63]
	v_exp_f32_e32 v96, v96
	v_exp_f32_e32 v97, v97
	v_exp_f32_e32 v98, v98
	v_exp_f32_e32 v99, v99
	v_mfma_f32_32x32x16_bf16 v[116:131], v[170:173], v[34:37], v[116:131]
	v_exp_f32_e32 v100, v100
	v_exp_f32_e32 v101, v101
	v_exp_f32_e32 v102, v102
	v_exp_f32_e32 v103, v103
	ds_read_b128 v[166:169], v146 offset:4096
	ds_read_b128 v[170:173], v147 offset:4096
	v_mfma_f32_32x32x16_bf16 v[80:95], v[174:177], v[158:161], v[80:95]
	v_exp_f32_e32 v104, v104
	v_exp_f32_e32 v105, v105
	v_add_f32_e32 v141, v141, v96
	v_add_f32_e32 v150, v150, v97
	v_add_f32_e32 v141, v141, v98
	v_add_f32_e32 v150, v150, v99
	v_mfma_f32_32x32x16_bf16 v[16:31], v[182:185], v[158:161], v[16:31]
	v_exp_f32_e32 v106, v106
	v_exp_f32_e32 v107, v107
	v_cvt_pk_bf16_f32 v158, v96, v97
	v_cvt_pk_bf16_f32 v159, v98, v99
	v_add_f32_e32 v141, v141, v100
	v_add_f32_e32 v150, v150, v101
	v_mfma_f32_32x32x16_bf16 v[80:95], v[178:181], v[162:165], v[80:95]
	v_exp_f32_e32 v108, v108
	v_exp_f32_e32 v109, v109
	v_cvt_pk_bf16_f32 v160, v100, v101
	v_cvt_pk_bf16_f32 v161, v102, v103
	v_add_f32_e32 v141, v141, v102
	v_add_f32_e32 v150, v150, v103
	v_mfma_f32_32x32x16_bf16 v[16:31], v[186:189], v[162:165], v[16:31]
	ds_read_b128 v[174:177], v146 offset:8192
	ds_read_b128 v[178:181], v147 offset:8192
	ds_read_b128 v[182:185], v146 offset:12288
	ds_read_b128 v[186:189], v147 offset:12288
	v_exp_f32_e32 v110, v110
	v_exp_f32_e32 v111, v111
	v_add_f32_e32 v141, v141, v104
	v_add_f32_e32 v150, v150, v105
	v_add_f32_e32 v141, v141, v106
	v_add_f32_e32 v150, v150, v107
	v_add_f32_e32 v141, v141, v108
	v_add_f32_e32 v150, v150, v109
	v_cvt_pk_bf16_f32 v162, v104, v105
	v_cvt_pk_bf16_f32 v163, v106, v107
	v_cvt_pk_bf16_f32 v164, v108, v109
	v_add_f32_e32 v141, v141, v110
	v_add_f32_e32 v150, v150, v111
	v_cvt_pk_bf16_f32 v165, v110, v111
	s_waitcnt lgkmcnt(4)
	v_mfma_f32_32x32x16_bf16 v[96:111], v[166:169], v[112:115], v[48:63]
	v_exp_f32_e32 v116, v116
	v_exp_f32_e32 v117, v117
	v_exp_f32_e32 v118, v118
	v_exp_f32_e32 v119, v119
	v_mfma_f32_32x32x16_bf16 v[96:111], v[170:173], v[42:45], v[96:111]
	v_exp_f32_e32 v120, v120
	v_exp_f32_e32 v121, v121
	v_exp_f32_e32 v122, v122
	v_exp_f32_e32 v123, v123
	ds_read_b128 v[166:169], v148 offset:4096
	ds_read_b128 v[170:173], v149 offset:4096
	s_waitcnt lgkmcnt(2)
	v_mfma_f32_32x32x16_bf16 v[64:79], v[174:177], v[158:161], v[64:79]
	v_exp_f32_e32 v124, v124
	v_exp_f32_e32 v125, v125
	v_add_f32_e32 v140, v140, v116
	v_add_f32_e32 v151, v151, v117
	v_add_f32_e32 v140, v140, v118
	v_add_f32_e32 v151, v151, v119
	v_mfma_f32_32x32x16_bf16 v[0:15], v[182:185], v[158:161], v[0:15]
	v_exp_f32_e32 v126, v126
	v_exp_f32_e32 v127, v127
	v_cvt_pk_bf16_f32 v158, v116, v117
	v_cvt_pk_bf16_f32 v159, v118, v119
	v_add_f32_e32 v140, v140, v120
	v_add_f32_e32 v151, v151, v121
	v_mfma_f32_32x32x16_bf16 v[64:79], v[178:181], v[162:165], v[64:79]
	v_exp_f32_e32 v128, v128
	v_exp_f32_e32 v129, v129
	v_cvt_pk_bf16_f32 v160, v120, v121
	v_cvt_pk_bf16_f32 v161, v122, v123
	v_add_f32_e32 v140, v140, v122
	v_add_f32_e32 v151, v151, v123
	v_mfma_f32_32x32x16_bf16 v[0:15], v[186:189], v[162:165], v[0:15]
	v_exp_f32_e32 v130, v130
	v_exp_f32_e32 v131, v131
	v_add_f32_e32 v140, v140, v124
	v_add_f32_e32 v151, v151, v125
	v_add_f32_e32 v140, v140, v126
	v_add_f32_e32 v151, v151, v127
	v_add_f32_e32 v140, v140, v128
	v_add_f32_e32 v151, v151, v129
	v_cvt_pk_bf16_f32 v162, v124, v125
	v_cvt_pk_bf16_f32 v163, v126, v127
	v_cvt_pk_bf16_f32 v164, v128, v129
	v_add_f32_e32 v140, v140, v130
	v_add_f32_e32 v151, v151, v131
	v_cvt_pk_bf16_f32 v165, v130, v131
	s_waitcnt lgkmcnt(0)
	v_mfma_f32_32x32x16_bf16 v[116:131], v[166:169], v[38:41], v[48:63]
	v_exp_f32_e32 v96, v96
	v_exp_f32_e32 v97, v97
	v_exp_f32_e32 v98, v98
	v_exp_f32_e32 v99, v99
	v_mfma_f32_32x32x16_bf16 v[116:131], v[170:173], v[34:37], v[116:131]
	v_exp_f32_e32 v100, v100
	v_exp_f32_e32 v101, v101
	v_exp_f32_e32 v102, v102
	v_exp_f32_e32 v103, v103
	ds_read_b128 v[166:169], v146 offset:16384
	ds_read_b128 v[170:173], v147 offset:16384
	v_mfma_f32_32x32x16_bf16 v[80:95], v[174:177], v[158:161], v[80:95]
	v_exp_f32_e32 v104, v104
	v_exp_f32_e32 v105, v105
	v_add_f32_e32 v141, v141, v96
	v_add_f32_e32 v150, v150, v97
	v_add_f32_e32 v141, v141, v98
	v_add_f32_e32 v150, v150, v99
	v_mfma_f32_32x32x16_bf16 v[16:31], v[182:185], v[158:161], v[16:31]
	v_exp_f32_e32 v106, v106
	v_exp_f32_e32 v107, v107
	v_cvt_pk_bf16_f32 v158, v96, v97
	v_cvt_pk_bf16_f32 v159, v98, v99
	v_add_f32_e32 v141, v141, v100
	v_add_f32_e32 v150, v150, v101
	v_mfma_f32_32x32x16_bf16 v[80:95], v[178:181], v[162:165], v[80:95]
	v_exp_f32_e32 v108, v108
	v_exp_f32_e32 v109, v109
	v_cvt_pk_bf16_f32 v160, v100, v101
	v_cvt_pk_bf16_f32 v161, v102, v103
	v_add_f32_e32 v141, v141, v102
	v_add_f32_e32 v150, v150, v103
	v_mfma_f32_32x32x16_bf16 v[16:31], v[186:189], v[162:165], v[16:31]
	ds_read_b128 v[174:177], v148 offset:8192
	ds_read_b128 v[178:181], v149 offset:8192
	ds_read_b128 v[182:185], v148 offset:12288
	ds_read_b128 v[186:189], v149 offset:12288
	v_exp_f32_e32 v110, v110
	v_exp_f32_e32 v111, v111
	v_add_f32_e32 v141, v141, v104
	v_add_f32_e32 v150, v150, v105
	v_add_f32_e32 v141, v141, v106
	v_add_f32_e32 v150, v150, v107
	v_add_f32_e32 v141, v141, v108
	v_add_f32_e32 v150, v150, v109
	v_cvt_pk_bf16_f32 v162, v104, v105
	v_cvt_pk_bf16_f32 v163, v106, v107
	v_cvt_pk_bf16_f32 v164, v108, v109
	v_add_f32_e32 v141, v141, v110
	v_add_f32_e32 v150, v150, v111
	v_cvt_pk_bf16_f32 v165, v110, v111
	s_waitcnt lgkmcnt(4)
; DI float ex2(float x) { return __builtin_amdgcn_exp2f(x); }
; #define MFMA32(a, b, c) __builtin_amdgcn_mfma_f32_32x32x16_bf16((a), (b), (c), 0, 0, 0)
; template <int MODE>
; DI void attn_unit(unsigned char* lds, const AttnParams& ap, int b, int h, int qb, int tid) {
;     ...
;     for (int c = 0; c < NCH; ++c) { *(u32x4*)(Ks0 + (c * 64 + lrow) * 72 + 8 * lch) = kreg[c]; *(u32x4*)(Vs0 + (c * 64 + lrow) * 72 + 8 * lch) = vreg[c]; }
;     __syncthreads();
;     if (n + NCH < ntiles) {
; #pragma unroll
;       for (int c = 0; c < NCH; ++c) { const int jn = (MODE == 2) ? jb - NCH - c : jb + NCH + c; kreg[c] = *(const u32x4*)(kg + (size_t)jn * 64 * PLD); vreg[c] = *(const u32x4*)(vg + (size_t)jn * 4096); } }
;     ...
;     if (MODE == 1) {
; #pragma unroll
;       for (int kh = 0; kh < 2; ++kh) {
;         const bf16_t* kb = Ks + (32 * kh + r32) * 72 + 8 * hi;
;         bf16x8 p0[2], p1[2];
;         { f32x16 s0 = splat16(ap.negM);
;           s0 = MFMA32(*(const bf16x8*)(kb), qf[0], s0); s0 = MFMA32(*(const bf16x8*)(kb + 16), qf[1], s0);
; #pragma unroll
;           for (int i = 0; i < 16; ++i) { s0[i] = ex2(s0[i]); l0 += s0[i]; }
;           p0[0] = pack8(s0, 0); p0[1] = pack8(s0, 1); }
;         { f32x16 s1 = splat16(ap.negM);
;           s1 = MFMA32(*(const bf16x8*)(kb + 32), qf[2], s1); s1 = MFMA32(*(const bf16x8*)(kb + 48), qf[3], s1);
; #pragma unroll
;           for (int i = 0; i < 16; ++i) { s1[i] = ex2(s1[i]); l1 += s1[i]; }
;           p1[0] = pack8(s1, 0); p1[1] = pack8(s1, 1); }
; #pragma unroll
;         for (int kk = 0; kk < 2; ++kk) {
; #pragma unroll
;           for (int eb = 0; eb < 2; ++eb) { const bf16_t* vb = Vs + (32 * eb + r32) * 72 + 32 * kh + 16 * kk + 8 * hi; const bf16x8 vf = *(const bf16x8*)vb;
;             O0[eb] = MFMA32(vf, p0[kk], O0[eb]); O1[eb] = MFMA32(vf, p1[kk], O1[eb]); } }
;       }
	v_mfma_f32_32x32x16_bf16 v[96:111], v[166:169], v[112:115], v[48:63]
	v_exp_f32_e32 v116, v116
	v_exp_f32_e32 v117, v117
	v_exp_f32_e32 v118, v118
	v_exp_f32_e32 v119, v119
	v_mfma_f32_32x32x16_bf16 v[96:111], v[170:173], v[42:45], v[96:111]
	v_exp_f32_e32 v120, v120
	v_exp_f32_e32 v121, v121
	v_exp_f32_e32 v122, v122
	v_exp_f32_e32 v123, v123
	ds_read_b128 v[166:169], v148 offset:16384
	ds_read_b128 v[170:173], v149 offset:16384
	s_waitcnt lgkmcnt(2)
	v_mfma_f32_32x32x16_bf16 v[64:79], v[174:177], v[158:161], v[64:79]
	v_exp_f32_e32 v124, v124
	v_exp_f32_e32 v125, v125
	v_add_f32_e32 v140, v140, v116
	v_add_f32_e32 v151, v151, v117
	v_add_f32_e32 v140, v140, v118
	v_add_f32_e32 v151, v151, v119
	v_mfma_f32_32x32x16_bf16 v[0:15], v[182:185], v[158:161], v[0:15]
	v_exp_f32_e32 v126, v126
	v_exp_f32_e32 v127, v127
	v_cvt_pk_bf16_f32 v158, v116, v117
	v_cvt_pk_bf16_f32 v159, v118, v119
	v_add_f32_e32 v140, v140, v120
	v_add_f32_e32 v151, v151, v121
	v_mfma_f32_32x32x16_bf16 v[64:79], v[178:181], v[162:165], v[64:79]
	v_exp_f32_e32 v128, v128
	v_exp_f32_e32 v129, v129
	v_cvt_pk_bf16_f32 v160, v120, v121
	v_cvt_pk_bf16_f32 v161, v122, v123
	v_add_f32_e32 v140, v140, v122
	v_add_f32_e32 v151, v151, v123
	v_mfma_f32_32x32x16_bf16 v[0:15], v[186:189], v[162:165], v[0:15]
	v_exp_f32_e32 v130, v130
	v_exp_f32_e32 v131, v131
	v_add_f32_e32 v140, v140, v124
	v_add_f32_e32 v151, v151, v125
	v_add_f32_e32 v140, v140, v126
	v_add_f32_e32 v151, v151, v127
	v_add_f32_e32 v140, v140, v128
	v_add_f32_e32 v151, v151, v129
	v_cvt_pk_bf16_f32 v162, v124, v125
	v_cvt_pk_bf16_f32 v163, v126, v127
	v_cvt_pk_bf16_f32 v164, v128, v129
	v_add_f32_e32 v140, v140, v130
	v_add_f32_e32 v151, v151, v131
	v_cvt_pk_bf16_f32 v165, v130, v131
	s_waitcnt vmcnt(0) lgkmcnt(0)
	s_cmp_le_u32 s4, s5
	s_barrier
	s_cbranch_scc1 .Lc_tile_ph1
	s_mov_b32 s9, 1
	s_branch .Lc_drain
.Lc_tile_ph1:
	s_add_i32 m0, s0, 0
	s_add_i32 s4, s4, 1
	global_load_lds_dwordx4 v32, s[2:3]
	s_add_i32 m0, s0, 8192
	s_add_u32 s2, s2, 0x68800
	s_addc_u32 s3, s3, 0
	global_load_lds_dwordx4 v157, s[10:11]
	s_add_u32 s10, s10, 0x2000
	s_addc_u32 s11, s11, 0
	s_waitcnt lgkmcnt(0)
	v_mfma_f32_32x32x16_bf16 v[116:131], v[166:169], v[38:41], v[48:63]
	v_exp_f32_e32 v96, v96
	v_exp_f32_e32 v97, v97
	v_exp_f32_e32 v98, v98
	v_exp_f32_e32 v99, v99
	v_mfma_f32_32x32x16_bf16 v[116:131], v[170:173], v[34:37], v[116:131]
	v_exp_f32_e32 v100, v100
	v_exp_f32_e32 v101, v101
	v_exp_f32_e32 v102, v102
	v_exp_f32_e32 v103, v103
	ds_read_b128 v[166:169], v146 offset:20480
	ds_read_b128 v[170:173], v147 offset:20480
	v_mfma_f32_32x32x16_bf16 v[80:95], v[174:177], v[158:161], v[80:95]
	v_exp_f32_e32 v104, v104
	v_exp_f32_e32 v105, v105
	v_add_f32_e32 v141, v141, v96
	v_add_f32_e32 v150, v150, v97
	v_add_f32_e32 v141, v141, v98
	v_add_f32_e32 v150, v150, v99
	v_mfma_f32_32x32x16_bf16 v[16:31], v[182:185], v[158:161], v[16:31]
	v_exp_f32_e32 v106, v106
	v_exp_f32_e32 v107, v107
	v_cvt_pk_bf16_f32 v158, v96, v97
	v_cvt_pk_bf16_f32 v159, v98, v99
	v_add_f32_e32 v141, v141, v100
	v_add_f32_e32 v150, v150, v101
	v_mfma_f32_32x32x16_bf16 v[80:95], v[178:181], v[162:165], v[80:95]
	v_exp_f32_e32 v108, v108
	v_exp_f32_e32 v109, v109
	v_cvt_pk_bf16_f32 v160, v100, v101
	v_cvt_pk_bf16_f32 v161, v102, v103
	v_add_f32_e32 v141, v141, v102
	v_add_f32_e32 v150, v150, v103
	v_mfma_f32_32x32x16_bf16 v[16:31], v[186:189], v[162:165], v[16:31]
	ds_read_b128 v[174:177], v146 offset:24576
	ds_read_b128 v[178:181], v147 offset:24576
	ds_read_b128 v[182:185], v146 offset:28672
	ds_read_b128 v[186:189], v147 offset:28672
	v_exp_f32_e32 v110, v110
	v_exp_f32_e32 v111, v111
	v_add_f32_e32 v141, v141, v104
	v_add_f32_e32 v150, v150, v105
	v_add_f32_e32 v141, v141, v106
	v_add_f32_e32 v150, v150, v107
	v_add_f32_e32 v141, v141, v108
	v_add_f32_e32 v150, v150, v109
	v_cvt_pk_bf16_f32 v162, v104, v105
	v_cvt_pk_bf16_f32 v163, v106, v107
	v_cvt_pk_bf16_f32 v164, v108, v109
	v_add_f32_e32 v141, v141, v110
	v_add_f32_e32 v150, v150, v111
	v_cvt_pk_bf16_f32 v165, v110, v111
	s_waitcnt lgkmcnt(4)
	v_mfma_f32_32x32x16_bf16 v[96:111], v[166:169], v[112:115], v[48:63]
	v_exp_f32_e32 v116, v116
	v_exp_f32_e32 v117, v117
	v_exp_f32_e32 v118, v118
	v_exp_f32_e32 v119, v119
	v_mfma_f32_32x32x16_bf16 v[96:111], v[170:173], v[42:45], v[96:111]
	v_exp_f32_e32 v120, v120
	v_exp_f32_e32 v121, v121
	v_exp_f32_e32 v122, v122
	v_exp_f32_e32 v123, v123
	ds_read_b128 v[166:169], v148 offset:20480
	ds_read_b128 v[170:173], v149 offset:20480
	s_waitcnt lgkmcnt(2)
	v_mfma_f32_32x32x16_bf16 v[64:79], v[174:177], v[158:161], v[64:79]
	v_exp_f32_e32 v124, v124
	v_exp_f32_e32 v125, v125
	v_add_f32_e32 v140, v140, v116
	v_add_f32_e32 v151, v151, v117
	v_add_f32_e32 v140, v140, v118
	v_add_f32_e32 v151, v151, v119
	v_mfma_f32_32x32x16_bf16 v[0:15], v[182:185], v[158:161], v[0:15]
	v_exp_f32_e32 v126, v126
	v_exp_f32_e32 v127, v127
	v_cvt_pk_bf16_f32 v158, v116, v117
	v_cvt_pk_bf16_f32 v159, v118, v119
	v_add_f32_e32 v140, v140, v120
	v_add_f32_e32 v151, v151, v121
	v_mfma_f32_32x32x16_bf16 v[64:79], v[178:181], v[162:165], v[64:79]
	v_exp_f32_e32 v128, v128
	v_exp_f32_e32 v129, v129
	v_cvt_pk_bf16_f32 v160, v120, v121
	v_cvt_pk_bf16_f32 v161, v122, v123
	v_add_f32_e32 v140, v140, v122
	v_add_f32_e32 v151, v151, v123
	v_mfma_f32_32x32x16_bf16 v[0:15], v[186:189], v[162:165], v[0:15]
	v_exp_f32_e32 v130, v130
	v_exp_f32_e32 v131, v131
	v_add_f32_e32 v140, v140, v124
	v_add_f32_e32 v151, v151, v125
	v_add_f32_e32 v140, v140, v126
	v_add_f32_e32 v151, v151, v127
	v_add_f32_e32 v140, v140, v128
	v_add_f32_e32 v151, v151, v129
	v_cvt_pk_bf16_f32 v162, v124, v125
	v_cvt_pk_bf16_f32 v163, v126, v127
	v_cvt_pk_bf16_f32 v164, v128, v129
	v_add_f32_e32 v140, v140, v130
	v_add_f32_e32 v151, v151, v131
	v_cvt_pk_bf16_f32 v165, v130, v131
	s_waitcnt lgkmcnt(0)
; DI float ex2(float x) { return __builtin_amdgcn_exp2f(x); }
; #define MFMA32(a, b, c) __builtin_amdgcn_mfma_f32_32x32x16_bf16((a), (b), (c), 0, 0, 0)
; template <int MODE>
; DI void attn_unit(unsigned char* lds, const AttnParams& ap, int b, int h, int qb, int tid) {
;     ...
;     for (int c = 0; c < NCH; ++c) { *(u32x4*)(Ks0 + (c * 64 + lrow) * 72 + 8 * lch) = kreg[c]; *(u32x4*)(Vs0 + (c * 64 + lrow) * 72 + 8 * lch) = vreg[c]; }
;     __syncthreads();
;     if (n + NCH < ntiles) {
; #pragma unroll
;       for (int c = 0; c < NCH; ++c) { const int jn = (MODE == 2) ? jb - NCH - c : jb + NCH + c; kreg[c] = *(const u32x4*)(kg + (size_t)jn * 64 * PLD); vreg[c] = *(const u32x4*)(vg + (size_t)jn * 4096); } }
;     ...
;     if (MODE == 1) {
; #pragma unroll
;       for (int kh = 0; kh < 2; ++kh) {
;         const bf16_t* kb = Ks + (32 * kh + r32) * 72 + 8 * hi;
;         bf16x8 p0[2], p1[2];
;         { f32x16 s0 = splat16(ap.negM);
;           s0 = MFMA32(*(const bf16x8*)(kb), qf[0], s0); s0 = MFMA32(*(const bf16x8*)(kb + 16), qf[1], s0);
; #pragma unroll
;           for (int i = 0; i < 16; ++i) { s0[i] = ex2(s0[i]); l0 += s0[i]; }
;           p0[0] = pack8(s0, 0); p0[1] = pack8(s0, 1); }
;         { f32x16 s1 = splat16(ap.negM);
;           s1 = MFMA32(*(const bf16x8*)(kb + 32), qf[2], s1); s1 = MFMA32(*(const bf16x8*)(kb + 48), qf[3], s1);
; #pragma unroll
;           for (int i = 0; i < 16; ++i) { s1[i] = ex2(s1[i]); l1 += s1[i]; }
;           p1[0] = pack8(s1, 0); p1[1] = pack8(s1, 1); }
; #pragma unroll
;         for (int kk = 0; kk < 2; ++kk) {
; #pragma unroll
;           for (int eb = 0; eb < 2; ++eb) { const bf16_t* vb = Vs + (32 * eb + r32) * 72 + 32 * kh + 16 * kk + 8 * hi; const bf16x8 vf = *(const bf16x8*)vb;
;             O0[eb] = MFMA32(vf, p0[kk], O0[eb]); O1[eb] = MFMA32(vf, p1[kk], O1[eb]); } }
;       }
	v_mfma_f32_32x32x16_bf16 v[116:131], v[166:169], v[38:41], v[48:63]
	v_exp_f32_e32 v96, v96
	v_exp_f32_e32 v97, v97
	v_exp_f32_e32 v98, v98
	v_exp_f32_e32 v99, v99
	v_mfma_f32_32x32x16_bf16 v[116:131], v[170:173], v[34:37], v[116:131]
	v_exp_f32_e32 v100, v100
	v_exp_f32_e32 v101, v101
	v_exp_f32_e32 v102, v102
	v_exp_f32_e32 v103, v103
	ds_read_b128 v[166:169], v146 offset:32768
	ds_read_b128 v[170:173], v147 offset:32768
	v_mfma_f32_32x32x16_bf16 v[80:95], v[174:177], v[158:161], v[80:95]
	v_exp_f32_e32 v104, v104
	v_exp_f32_e32 v105, v105
	v_add_f32_e32 v141, v141, v96
	v_add_f32_e32 v150, v150, v97
	v_add_f32_e32 v141, v141, v98
	v_add_f32_e32 v150, v150, v99
	v_mfma_f32_32x32x16_bf16 v[16:31], v[182:185], v[158:161], v[16:31]
	v_exp_f32_e32 v106, v106
	v_exp_f32_e32 v107, v107
	v_cvt_pk_bf16_f32 v158, v96, v97
	v_cvt_pk_bf16_f32 v159, v98, v99
	v_add_f32_e32 v141, v141, v100
	v_add_f32_e32 v150, v150, v101
	v_mfma_f32_32x32x16_bf16 v[80:95], v[178:181], v[162:165], v[80:95]
	v_exp_f32_e32 v108, v108
	v_exp_f32_e32 v109, v109
	v_cvt_pk_bf16_f32 v160, v100, v101
	v_cvt_pk_bf16_f32 v161, v102, v103
	v_add_f32_e32 v141, v141, v102
	v_add_f32_e32 v150, v150, v103
	v_mfma_f32_32x32x16_bf16 v[16:31], v[186:189], v[162:165], v[16:31]
	ds_read_b128 v[174:177], v148 offset:24576
	ds_read_b128 v[178:181], v149 offset:24576
	ds_read_b128 v[182:185], v148 offset:28672
	ds_read_b128 v[186:189], v149 offset:28672
	v_exp_f32_e32 v110, v110
	v_exp_f32_e32 v111, v111
	v_add_f32_e32 v141, v141, v104
	v_add_f32_e32 v150, v150, v105
	v_add_f32_e32 v141, v141, v106
	v_add_f32_e32 v150, v150, v107
	v_add_f32_e32 v141, v141, v108
	v_add_f32_e32 v150, v150, v109
	v_cvt_pk_bf16_f32 v162, v104, v105
	v_cvt_pk_bf16_f32 v163, v106, v107
	v_cvt_pk_bf16_f32 v164, v108, v109
	v_add_f32_e32 v141, v141, v110
	v_add_f32_e32 v150, v150, v111
	v_cvt_pk_bf16_f32 v165, v110, v111
	s_waitcnt lgkmcnt(4)
	v_mfma_f32_32x32x16_bf16 v[96:111], v[166:169], v[112:115], v[48:63]
	v_exp_f32_e32 v116, v116
	v_exp_f32_e32 v117, v117
	v_exp_f32_e32 v118, v118
	v_exp_f32_e32 v119, v119
	v_mfma_f32_32x32x16_bf16 v[96:111], v[170:173], v[42:45], v[96:111]
	v_exp_f32_e32 v120, v120
	v_exp_f32_e32 v121, v121
	v_exp_f32_e32 v122, v122
	v_exp_f32_e32 v123, v123
	ds_read_b128 v[166:169], v148 offset:32768
	ds_read_b128 v[170:173], v149 offset:32768
	s_waitcnt lgkmcnt(2)
	v_mfma_f32_32x32x16_bf16 v[64:79], v[174:177], v[158:161], v[64:79]
	v_exp_f32_e32 v124, v124
	v_exp_f32_e32 v125, v125
	v_add_f32_e32 v140, v140, v116
	v_add_f32_e32 v151, v151, v117
	v_add_f32_e32 v140, v140, v118
	v_add_f32_e32 v151, v151, v119
	v_mfma_f32_32x32x16_bf16 v[0:15], v[182:185], v[158:161], v[0:15]
	v_exp_f32_e32 v126, v126
	v_exp_f32_e32 v127, v127
	v_cvt_pk_bf16_f32 v158, v116, v117
	v_cvt_pk_bf16_f32 v159, v118, v119
	v_add_f32_e32 v140, v140, v120
	v_add_f32_e32 v151, v151, v121
	v_mfma_f32_32x32x16_bf16 v[64:79], v[178:181], v[162:165], v[64:79]
	v_exp_f32_e32 v128, v128
	v_exp_f32_e32 v129, v129
	v_cvt_pk_bf16_f32 v160, v120, v121
	v_cvt_pk_bf16_f32 v161, v122, v123
	v_add_f32_e32 v140, v140, v122
	v_add_f32_e32 v151, v151, v123
	v_mfma_f32_32x32x16_bf16 v[0:15], v[186:189], v[162:165], v[0:15]
	v_exp_f32_e32 v130, v130
	v_exp_f32_e32 v131, v131
	v_add_f32_e32 v140, v140, v124
	v_add_f32_e32 v151, v151, v125
	v_add_f32_e32 v140, v140, v126
	v_add_f32_e32 v151, v151, v127
	v_add_f32_e32 v140, v140, v128
	v_add_f32_e32 v151, v151, v129
	v_cvt_pk_bf16_f32 v162, v124, v125
	v_cvt_pk_bf16_f32 v163, v126, v127
	v_cvt_pk_bf16_f32 v164, v128, v129
	v_add_f32_e32 v140, v140, v130
	v_add_f32_e32 v151, v151, v131
	v_cvt_pk_bf16_f32 v165, v130, v131
	s_waitcnt vmcnt(0) lgkmcnt(0)
	s_cmp_le_u32 s4, s5
	s_barrier
	s_cbranch_scc1 .Lc_tile_ph2
	s_mov_b32 s9, 2
	s_branch .Lc_drain
.Lc_tile_ph2:
	s_add_i32 m0, s0, 16384
	s_add_i32 s4, s4, 1
	global_load_lds_dwordx4 v32, s[2:3]
	s_add_i32 m0, s0, 24576
	s_add_u32 s2, s2, 0x68800
	s_addc_u32 s3, s3, 0
	global_load_lds_dwordx4 v157, s[10:11]
	s_add_u32 s10, s10, 0x2000
	s_addc_u32 s11, s11, 0
	s_waitcnt lgkmcnt(0)
	v_mfma_f32_32x32x16_bf16 v[116:131], v[166:169], v[38:41], v[48:63]
	v_exp_f32_e32 v96, v96
	v_exp_f32_e32 v97, v97
	v_exp_f32_e32 v98, v98
	v_exp_f32_e32 v99, v99
	v_mfma_f32_32x32x16_bf16 v[116:131], v[170:173], v[34:37], v[116:131]
	v_exp_f32_e32 v100, v100
	v_exp_f32_e32 v101, v101
	v_exp_f32_e32 v102, v102
	v_exp_f32_e32 v103, v103
	ds_read_b128 v[166:169], v146 offset:36864
	ds_read_b128 v[170:173], v147 offset:36864
	v_mfma_f32_32x32x16_bf16 v[80:95], v[174:177], v[158:161], v[80:95]
	v_exp_f32_e32 v104, v104
	v_exp_f32_e32 v105, v105
	v_add_f32_e32 v141, v141, v96
	v_add_f32_e32 v150, v150, v97
	v_add_f32_e32 v141, v141, v98
	v_add_f32_e32 v150, v150, v99
	v_mfma_f32_32x32x16_bf16 v[16:31], v[182:185], v[158:161], v[16:31]
	v_exp_f32_e32 v106, v106
	v_exp_f32_e32 v107, v107
	v_cvt_pk_bf16_f32 v158, v96, v97
	v_cvt_pk_bf16_f32 v159, v98, v99
	v_add_f32_e32 v141, v141, v100
	v_add_f32_e32 v150, v150, v101
	v_mfma_f32_32x32x16_bf16 v[80:95], v[178:181], v[162:165], v[80:95]
	v_exp_f32_e32 v108, v108
	v_exp_f32_e32 v109, v109
	v_cvt_pk_bf16_f32 v160, v100, v101
	v_cvt_pk_bf16_f32 v161, v102, v103
	v_add_f32_e32 v141, v141, v102
	v_add_f32_e32 v150, v150, v103
	v_mfma_f32_32x32x16_bf16 v[16:31], v[186:189], v[162:165], v[16:31]
	ds_read_b128 v[174:177], v146 offset:40960
	ds_read_b128 v[178:181], v147 offset:40960
	ds_read_b128 v[182:185], v146 offset:45056
	ds_read_b128 v[186:189], v147 offset:45056
	v_exp_f32_e32 v110, v110
	v_exp_f32_e32 v111, v111
	v_add_f32_e32 v141, v141, v104
	v_add_f32_e32 v150, v150, v105
	v_add_f32_e32 v141, v141, v106
	v_add_f32_e32 v150, v150, v107
	v_add_f32_e32 v141, v141, v108
	v_add_f32_e32 v150, v150, v109
	v_cvt_pk_bf16_f32 v162, v104, v105
	v_cvt_pk_bf16_f32 v163, v106, v107
	v_cvt_pk_bf16_f32 v164, v108, v109
	v_add_f32_e32 v141, v141, v110
	v_add_f32_e32 v150, v150, v111
	v_cvt_pk_bf16_f32 v165, v110, v111
	s_waitcnt lgkmcnt(4)
; DI float ex2(float x) { return __builtin_amdgcn_exp2f(x); }
; #define MFMA32(a, b, c) __builtin_amdgcn_mfma_f32_32x32x16_bf16((a), (b), (c), 0, 0, 0)
; template <int MODE>
; DI void attn_unit(unsigned char* lds, const AttnParams& ap, int b, int h, int qb, int tid) {
;     ...
;     if (MODE == 1) {
; #pragma unroll
;       for (int kh = 0; kh < 2; ++kh) {
;         const bf16_t* kb = Ks + (32 * kh + r32) * 72 + 8 * hi;
;         bf16x8 p0[2], p1[2];
;         { f32x16 s0 = splat16(ap.negM);
;           s0 = MFMA32(*(const bf16x8*)(kb), qf[0], s0); s0 = MFMA32(*(const bf16x8*)(kb + 16), qf[1], s0);
; #pragma unroll
;           for (int i = 0; i < 16; ++i) { s0[i] = ex2(s0[i]); l0 += s0[i]; }
;           p0[0] = pack8(s0, 0); p0[1] = pack8(s0, 1); }
;         { f32x16 s1 = splat16(ap.negM);
;           s1 = MFMA32(*(const bf16x8*)(kb + 32), qf[2], s1); s1 = MFMA32(*(const bf16x8*)(kb + 48), qf[3], s1);
; #pragma unroll
;           for (int i = 0; i < 16; ++i) { s1[i] = ex2(s1[i]); l1 += s1[i]; }
;           p1[0] = pack8(s1, 0); p1[1] = pack8(s1, 1); }
; #pragma unroll
;         for (int kk = 0; kk < 2; ++kk) {
; #pragma unroll
;           for (int eb = 0; eb < 2; ++eb) { const bf16_t* vb = Vs + (32 * eb + r32) * 72 + 32 * kh + 16 * kk + 8 * hi; const bf16x8 vf = *(const bf16x8*)vb;
;             O0[eb] = MFMA32(vf, p0[kk], O0[eb]); O1[eb] = MFMA32(vf, p1[kk], O1[eb]); } }
;       }
	v_mfma_f32_32x32x16_bf16 v[96:111], v[166:169], v[112:115], v[48:63]
	v_exp_f32_e32 v116, v116
	v_exp_f32_e32 v117, v117
	v_exp_f32_e32 v118, v118
	v_exp_f32_e32 v119, v119
	v_mfma_f32_32x32x16_bf16 v[96:111], v[170:173], v[42:45], v[96:111]
	v_exp_f32_e32 v120, v120
	v_exp_f32_e32 v121, v121
	v_exp_f32_e32 v122, v122
	v_exp_f32_e32 v123, v123
	ds_read_b128 v[166:169], v148 offset:36864
	ds_read_b128 v[170:173], v149 offset:36864
	s_waitcnt lgkmcnt(2)
	v_mfma_f32_32x32x16_bf16 v[64:79], v[174:177], v[158:161], v[64:79]
	v_exp_f32_e32 v124, v124
	v_exp_f32_e32 v125, v125
	v_add_f32_e32 v140, v140, v116
	v_add_f32_e32 v151, v151, v117
	v_add_f32_e32 v140, v140, v118
	v_add_f32_e32 v151, v151, v119
	v_mfma_f32_32x32x16_bf16 v[0:15], v[182:185], v[158:161], v[0:15]
	v_exp_f32_e32 v126, v126
	v_exp_f32_e32 v127, v127
	v_cvt_pk_bf16_f32 v158, v116, v117
	v_cvt_pk_bf16_f32 v159, v118, v119
	v_add_f32_e32 v140, v140, v120
	v_add_f32_e32 v151, v151, v121
	v_mfma_f32_32x32x16_bf16 v[64:79], v[178:181], v[162:165], v[64:79]
	v_exp_f32_e32 v128, v128
	v_exp_f32_e32 v129, v129
	v_cvt_pk_bf16_f32 v160, v120, v121
	v_cvt_pk_bf16_f32 v161, v122, v123
	v_add_f32_e32 v140, v140, v122
	v_add_f32_e32 v151, v151, v123
	v_mfma_f32_32x32x16_bf16 v[0:15], v[186:189], v[162:165], v[0:15]
	v_exp_f32_e32 v130, v130
	v_exp_f32_e32 v131, v131
	v_add_f32_e32 v140, v140, v124
	v_add_f32_e32 v151, v151, v125
	v_add_f32_e32 v140, v140, v126
	v_add_f32_e32 v151, v151, v127
	v_add_f32_e32 v140, v140, v128
	v_add_f32_e32 v151, v151, v129
	v_cvt_pk_bf16_f32 v162, v124, v125
	v_cvt_pk_bf16_f32 v163, v126, v127
	v_cvt_pk_bf16_f32 v164, v128, v129
	v_add_f32_e32 v140, v140, v130
	v_add_f32_e32 v151, v151, v131
	v_cvt_pk_bf16_f32 v165, v130, v131
	s_waitcnt lgkmcnt(0)
	v_mfma_f32_32x32x16_bf16 v[116:131], v[166:169], v[38:41], v[48:63]
	v_exp_f32_e32 v96, v96
	v_exp_f32_e32 v97, v97
	v_exp_f32_e32 v98, v98
	v_exp_f32_e32 v99, v99
	v_mfma_f32_32x32x16_bf16 v[116:131], v[170:173], v[34:37], v[116:131]
	v_exp_f32_e32 v100, v100
	v_exp_f32_e32 v101, v101
	v_exp_f32_e32 v102, v102
	v_exp_f32_e32 v103, v103
	ds_read_b128 v[166:169], v146
	ds_read_b128 v[170:173], v147
	v_mfma_f32_32x32x16_bf16 v[80:95], v[174:177], v[158:161], v[80:95]
	v_exp_f32_e32 v104, v104
	v_exp_f32_e32 v105, v105
	v_add_f32_e32 v141, v141, v96
	v_add_f32_e32 v150, v150, v97
	v_add_f32_e32 v141, v141, v98
	v_add_f32_e32 v150, v150, v99
	v_mfma_f32_32x32x16_bf16 v[16:31], v[182:185], v[158:161], v[16:31]
	v_exp_f32_e32 v106, v106
	v_exp_f32_e32 v107, v107
	v_cvt_pk_bf16_f32 v158, v96, v97
	v_cvt_pk_bf16_f32 v159, v98, v99
	v_add_f32_e32 v141, v141, v100
	v_add_f32_e32 v150, v150, v101
	v_mfma_f32_32x32x16_bf16 v[80:95], v[178:181], v[162:165], v[80:95]
	v_exp_f32_e32 v108, v108
	v_exp_f32_e32 v109, v109
	v_cvt_pk_bf16_f32 v160, v100, v101
	v_cvt_pk_bf16_f32 v161, v102, v103
	v_add_f32_e32 v141, v141, v102
	v_add_f32_e32 v150, v150, v103
	v_mfma_f32_32x32x16_bf16 v[16:31], v[186:189], v[162:165], v[16:31]
	ds_read_b128 v[174:177], v148 offset:40960
	ds_read_b128 v[178:181], v149 offset:40960
	ds_read_b128 v[182:185], v148 offset:45056
	ds_read_b128 v[186:189], v149 offset:45056
	v_exp_f32_e32 v110, v110
	v_exp_f32_e32 v111, v111
	v_add_f32_e32 v141, v141, v104
	v_add_f32_e32 v150, v150, v105
	v_add_f32_e32 v141, v141, v106
	v_add_f32_e32 v150, v150, v107
	v_add_f32_e32 v141, v141, v108
	v_add_f32_e32 v150, v150, v109
	v_cvt_pk_bf16_f32 v162, v104, v105
	v_cvt_pk_bf16_f32 v163, v106, v107
	v_cvt_pk_bf16_f32 v164, v108, v109
	v_add_f32_e32 v141, v141, v110
	v_add_f32_e32 v150, v150, v111
	v_cvt_pk_bf16_f32 v165, v110, v111
	s_waitcnt lgkmcnt(4)
	v_mfma_f32_32x32x16_bf16 v[96:111], v[166:169], v[112:115], v[48:63]
	v_exp_f32_e32 v116, v116
	v_exp_f32_e32 v117, v117
	v_exp_f32_e32 v118, v118
	v_exp_f32_e32 v119, v119
	v_mfma_f32_32x32x16_bf16 v[96:111], v[170:173], v[42:45], v[96:111]
	v_exp_f32_e32 v120, v120
	v_exp_f32_e32 v121, v121
	v_exp_f32_e32 v122, v122
	v_exp_f32_e32 v123, v123
	ds_read_b128 v[166:169], v148
	ds_read_b128 v[170:173], v149
	s_waitcnt lgkmcnt(2)
	v_mfma_f32_32x32x16_bf16 v[64:79], v[174:177], v[158:161], v[64:79]
	v_exp_f32_e32 v124, v124
	v_exp_f32_e32 v125, v125
	v_add_f32_e32 v140, v140, v116
	v_add_f32_e32 v151, v151, v117
	v_add_f32_e32 v140, v140, v118
	v_add_f32_e32 v151, v151, v119
	v_mfma_f32_32x32x16_bf16 v[0:15], v[182:185], v[158:161], v[0:15]
	v_exp_f32_e32 v126, v126
	v_exp_f32_e32 v127, v127
	v_cvt_pk_bf16_f32 v158, v116, v117
	v_cvt_pk_bf16_f32 v159, v118, v119
	v_add_f32_e32 v140, v140, v120
	v_add_f32_e32 v151, v151, v121
	v_mfma_f32_32x32x16_bf16 v[64:79], v[178:181], v[162:165], v[64:79]
	v_exp_f32_e32 v128, v128
	v_exp_f32_e32 v129, v129
	v_cvt_pk_bf16_f32 v160, v120, v121
	v_cvt_pk_bf16_f32 v161, v122, v123
	v_add_f32_e32 v140, v140, v122
	v_add_f32_e32 v151, v151, v123
	v_mfma_f32_32x32x16_bf16 v[0:15], v[186:189], v[162:165], v[0:15]
	v_exp_f32_e32 v130, v130
	v_exp_f32_e32 v131, v131
	v_add_f32_e32 v140, v140, v124
	v_add_f32_e32 v151, v151, v125
	v_add_f32_e32 v140, v140, v126
	v_add_f32_e32 v151, v151, v127
	v_add_f32_e32 v140, v140, v128
	v_add_f32_e32 v151, v151, v129
	v_cvt_pk_bf16_f32 v162, v124, v125
	v_cvt_pk_bf16_f32 v163, v126, v127
	v_cvt_pk_bf16_f32 v164, v128, v129
	v_add_f32_e32 v140, v140, v130
	v_add_f32_e32 v151, v151, v131
	v_cvt_pk_bf16_f32 v165, v130, v131
	s_waitcnt vmcnt(0) lgkmcnt(0)
	s_cmp_le_u32 s4, s5
	s_barrier
	s_cbranch_scc1 .Lc_tile_ph0
	s_mov_b32 s9, 0

; template <int MODE>
; DI void attn_unit(unsigned char* lds, const AttnParams& ap, int b, int h, int qb, int tid) {
;     ...
;   for (int n = 0; n < ntiles; n += NCH) {
;     const int jb = (MODE == 2) ? jhi - n : jlo + n;
;     __syncthreads();
;     if (MODE == 2 && D_EARLY) { int alld = 1;
; #pragma unroll
;       for (int w = 0; w < 8; ++w) alld &= flags[w];
;       if (alld) break; }
; #pragma unroll
;     for (int c = 0; c < NCH; ++c) { *(u32x4*)(Ks0 + (c * 64 + lrow) * 72 + 8 * lch) = kreg[c]; *(u32x4*)(Vs0 + (c * 64 + lrow) * 72 + 8 * lch) = vreg[c]; }
;     __syncthreads();
;     if (n + NCH < ntiles) {
; #pragma unroll
;       for (int c = 0; c < NCH; ++c) { const int jn = (MODE == 2) ? jb - NCH - c : jb + NCH + c; kreg[c] = *(const u32x4*)(kg + (size_t)jn * 64 * PLD); vreg[c] = *(const u32x4*)(vg + (size_t)jn * 4096); } }
.Lc_idle_ph0:
	s_add_i32 m0, s0, 32768
	s_add_i32 s4, s4, 1
	global_load_lds_dwordx4 v32, s[2:3]
	s_add_i32 m0, s0, 40960
	s_add_u32 s2, s2, 0x68800
	s_addc_u32 s3, s3, 0
	global_load_lds_dwordx4 v157, s[10:11]
	s_add_u32 s10, s10, 0x2000
	s_addc_u32 s11, s11, 0
	s_waitcnt vmcnt(0) lgkmcnt(0)
	s_cmp_gt_u32 s4, s8
	s_barrier
	s_cbranch_scc1 .Lc_tiles_done
.Lc_idle_ph1:
	s_add_i32 m0, s0, 0
	s_add_i32 s4, s4, 1
	global_load_lds_dwordx4 v32, s[2:3]
	s_add_i32 m0, s0, 8192
	s_add_u32 s2, s2, 0x68800
	s_addc_u32 s3, s3, 0
	global_load_lds_dwordx4 v157, s[10:11]
	s_add_u32 s10, s10, 0x2000
	s_addc_u32 s11, s11, 0
	s_waitcnt vmcnt(0) lgkmcnt(0)
	s_cmp_gt_u32 s4, s8
	s_barrier
	s_cbranch_scc1 .Lc_tiles_done
.Lc_idle_ph2:
	s_add_i32 m0, s0, 16384
	s_add_i32 s4, s4, 1
	global_load_lds_dwordx4 v32, s[2:3]
	s_add_i32 m0, s0, 24576
	s_add_u32 s2, s2, 0x68800
	s_addc_u32 s3, s3, 0
	global_load_lds_dwordx4 v157, s[10:11]
	s_add_u32 s10, s10, 0x2000
	s_addc_u32 s11, s11, 0
	s_waitcnt vmcnt(0) lgkmcnt(0)
	s_cmp_gt_u32 s4, s8
	s_barrier
	s_cbranch_scc1 .Lc_tiles_done
	s_branch .Lc_idle_ph0
